# grid barrier release flattened: followers poll the cross-XCC generation word directly; per-XCC release add removed
# speedup vs baseline: 1.0089x; 1.0041x over previous
; __device__ __forceinline__ unsigned xb_ld(unsigned* p)              { return __hip_atomic_load(p, __ATOMIC_RELAXED, __HIP_MEMORY_SCOPE_AGENT); }
; __device__ __forceinline__ unsigned xb_add(unsigned* p, unsigned v) { return __hip_atomic_fetch_add(p, v, __ATOMIC_RELAXED, __HIP_MEMORY_SCOPE_AGENT); }
; #define XB_SPIN(cond, bar) do { unsigned _sp = 0; while (cond) { __builtin_amdgcn_s_sleep(1); \
;     if ((++_sp & 255u) == 0u) { if (xb_ld(&(bar)[XB_TMO])) break; if (_sp > XB_SPIN_CAP) { atomicAdd(&(bar)[XB_TMO], 1u); break; } } } } while (0)
; __device__ __forceinline__ void xcd_barrier(const XcdBarrier& b, const bool leader  ) {
;     ...
;         const unsigned old = xb_add(&bar[XB_XSUB(b.x)], 1u);
;         const unsigned gen = old / nloc;
;         if (old + 1u == (gen + 1u) * nloc) {
;             __builtin_amdgcn_fence(__ATOMIC_RELEASE, "agent");
;             asm volatile("s_waitcnt vmcnt(0)" ::: "memory");
;             const unsigned og = xb_add(&bar[XB_TOP], 1u);
;             const unsigned tg = og / nx;
;             if (og + 1u == (tg + 1u) * nx) xb_add(&bar[XB_TOPGEN], 1u);
;             else XB_SPIN(xb_ld(&bar[XB_TOPGEN]) == tg, bar);
;             __builtin_amdgcn_fence(__ATOMIC_ACQUIRE, "agent");
;             xb_add(&bar[XB_XGEN(b.x)], 1u);
;             asm volatile("s_waitcnt vmcnt(0)" ::: "memory");
;         } else {
;             XB_SPIN(xb_ld(&bar[XB_XGEN(b.x)]) == gen, bar);
;             __builtin_amdgcn_fence(__ATOMIC_ACQUIRE, "agent");
;             asm volatile("s_waitcnt vmcnt(0)" ::: "memory");
;         }
.LBB0_86:
	s_or_b64 exec, exec, s[12:13]
	v_cvt_f32_u32_e32 v4, v2
	s_waitcnt vmcnt(0)
	v_readfirstlane_b32 s10, v3
	s_add_u32 s2, s2, 0x2400
	s_addc_u32 s3, s3, 0
	v_rcp_iflag_f32_e32 v4, v4
	v_add_u32_e32 v5, s10, v1
	v_mul_f32_e32 v3, 0x4f7ffffe, v4
	v_cvt_u32_f32_e32 v3, v3
	v_sub_u32_e32 v4, 0, v2
	v_mul_lo_u32 v1, v4, v3
	v_mul_hi_u32 v1, v3, v1
	v_add_u32_e32 v1, v3, v1
	v_mul_hi_u32 v1, v5, v1
	v_mul_lo_u32 v3, v1, v2
	v_sub_u32_e32 v3, v5, v3
	v_add_u32_e32 v4, 1, v1
	v_cmp_ge_u32_e32 vcc, v3, v2
	s_nop 1
	v_cndmask_b32_e32 v1, v1, v4, vcc
	v_sub_u32_e32 v4, v3, v2
	v_cndmask_b32_e32 v3, v3, v4, vcc
	v_add_u32_e32 v4, 1, v1
	v_cmp_ge_u32_e32 vcc, v3, v2
	v_add_u32_e32 v3, 1, v5
	s_nop 0
	v_cndmask_b32_e32 v1, v1, v4, vcc
	v_mul_lo_u32 v4, v2, v1
	v_add_u32_e32 v2, v4, v2
	v_cmp_ne_u32_e32 vcc, v3, v2
	s_and_saveexec_b64 s[10:11], vcc
	s_xor_b64 s[10:11], exec, s[10:11]
	s_cbranch_execz .LBB0_100
	s_waitcnt lgkmcnt(0)
	v_mov_b32_e32 v0, 0
	s_add_u32 s2, s8, 0x7500
	s_addc_u32 s3, s9, 0
	global_load_dword v2, v0, s[2:3] sc1
	s_waitcnt vmcnt(0)
	v_cmp_eq_u32_e32 vcc, v2, v1
	s_and_saveexec_b64 s[12:13], vcc
	s_cbranch_execz .LBB0_99
	s_mov_b32 s20, 1
	s_mov_b64 s[14:15], 0
	s_branch .LBB0_90

; __device__ __forceinline__ unsigned xb_add(unsigned* p, unsigned v) { return __hip_atomic_fetch_add(p, v, __ATOMIC_RELAXED, __HIP_MEMORY_SCOPE_AGENT); }
; __device__ __forceinline__ void xcd_barrier(const XcdBarrier& b, const bool leader  ) {
;     ...
;             __builtin_amdgcn_fence(__ATOMIC_ACQUIRE, "agent");
;             xb_add(&bar[XB_XGEN(b.x)], 1u);
;             asm volatile("s_waitcnt vmcnt(0)" ::: "memory");
.LBB0_117:
	s_or_b64 exec, exec, s[6:7]
	s_mov_b64 s[6:7], exec
	v_mbcnt_lo_u32_b32 v0, s6, 0
	v_mbcnt_hi_u32_b32 v0, s7, v0
	v_cmp_eq_u32_e32 vcc, 0, v0
	s_waitcnt vmcnt(0)
	buffer_inv sc1
	s_and_saveexec_b64 s[8:9], vcc
	s_cbranch_execz .LBB0_119
	s_bcnt1_i32_b64 s6, s[6:7]
	v_mov_b32_e32 v0, 0
	v_mov_b32_e32 v1, s6
	s_nop 0

; __device__ __forceinline__ unsigned xb_ld(unsigned* p)              { return __hip_atomic_load(p, __ATOMIC_RELAXED, __HIP_MEMORY_SCOPE_AGENT); }
; __device__ __forceinline__ unsigned xb_add(unsigned* p, unsigned v) { return __hip_atomic_fetch_add(p, v, __ATOMIC_RELAXED, __HIP_MEMORY_SCOPE_AGENT); }
; #define XB_SPIN(cond, bar) do { unsigned _sp = 0; while (cond) { __builtin_amdgcn_s_sleep(1); \
;     if ((++_sp & 255u) == 0u) { if (xb_ld(&(bar)[XB_TMO])) break; if (_sp > XB_SPIN_CAP) { atomicAdd(&(bar)[XB_TMO], 1u); break; } } } } while (0)
; __device__ __forceinline__ void xcd_barrier(const XcdBarrier& b, const bool leader  ) {
;     ...
;         const unsigned old = xb_add(&bar[XB_XSUB(b.x)], 1u);
;         const unsigned gen = old / nloc;
;         if (old + 1u == (gen + 1u) * nloc) {
;             __builtin_amdgcn_fence(__ATOMIC_RELEASE, "agent");
;             asm volatile("s_waitcnt vmcnt(0)" ::: "memory");
;             const unsigned og = xb_add(&bar[XB_TOP], 1u);
;             const unsigned tg = og / nx;
;             if (og + 1u == (tg + 1u) * nx) xb_add(&bar[XB_TOPGEN], 1u);
;             else XB_SPIN(xb_ld(&bar[XB_TOPGEN]) == tg, bar);
;             __builtin_amdgcn_fence(__ATOMIC_ACQUIRE, "agent");
;             xb_add(&bar[XB_XGEN(b.x)], 1u);
;             asm volatile("s_waitcnt vmcnt(0)" ::: "memory");
;         } else {
;             XB_SPIN(xb_ld(&bar[XB_XGEN(b.x)]) == gen, bar);
;             __builtin_amdgcn_fence(__ATOMIC_ACQUIRE, "agent");
;             asm volatile("s_waitcnt vmcnt(0)" ::: "memory");
;         }
.LBB0_153:
	s_or_b64 exec, exec, s[12:13]
	v_cvt_f32_u32_e32 v4, v2
	s_waitcnt vmcnt(0)
	v_readfirstlane_b32 s10, v3
	s_add_u32 s8, s8, 0x2400
	s_addc_u32 s9, s9, 0
	v_rcp_iflag_f32_e32 v4, v4
	v_add_u32_e32 v5, s10, v1
	v_mul_f32_e32 v3, 0x4f7ffffe, v4
	v_cvt_u32_f32_e32 v3, v3
	v_sub_u32_e32 v4, 0, v2
	v_mul_lo_u32 v1, v4, v3
	v_mul_hi_u32 v1, v3, v1
	v_add_u32_e32 v1, v3, v1
	v_mul_hi_u32 v1, v5, v1
	v_mul_lo_u32 v3, v1, v2
	v_sub_u32_e32 v3, v5, v3
	v_add_u32_e32 v4, 1, v1
	v_cmp_ge_u32_e32 vcc, v3, v2
	s_nop 1
	v_cndmask_b32_e32 v1, v1, v4, vcc
	v_sub_u32_e32 v4, v3, v2
	v_cndmask_b32_e32 v3, v3, v4, vcc
	v_add_u32_e32 v4, 1, v1
	v_cmp_ge_u32_e32 vcc, v3, v2
	v_add_u32_e32 v3, 1, v5
	s_nop 0
	v_cndmask_b32_e32 v1, v1, v4, vcc
	v_mul_lo_u32 v4, v2, v1
	v_add_u32_e32 v2, v4, v2
	v_cmp_ne_u32_e32 vcc, v3, v2
	s_and_saveexec_b64 s[10:11], vcc
	s_xor_b64 s[10:11], exec, s[10:11]
	s_cbranch_execz .LBB0_167
	s_waitcnt lgkmcnt(0)
	v_mov_b32_e32 v0, 0
	s_add_u32 s8, s6, 0x7500
	s_addc_u32 s9, s7, 0
	global_load_dword v2, v0, s[8:9] sc1
	s_waitcnt vmcnt(0)
	v_cmp_eq_u32_e32 vcc, v2, v1
	s_and_saveexec_b64 s[12:13], vcc
	s_cbranch_execz .LBB0_166
	s_mov_b32 s20, 1
	s_mov_b64 s[14:15], 0
	s_branch .LBB0_157

; __device__ __forceinline__ unsigned xb_add(unsigned* p, unsigned v) { return __hip_atomic_fetch_add(p, v, __ATOMIC_RELAXED, __HIP_MEMORY_SCOPE_AGENT); }
; __device__ __forceinline__ void xcd_barrier(const XcdBarrier& b, const bool leader  ) {
;     ...
;             __builtin_amdgcn_fence(__ATOMIC_ACQUIRE, "agent");
;             xb_add(&bar[XB_XGEN(b.x)], 1u);
;             asm volatile("s_waitcnt vmcnt(0)" ::: "memory");
.LBB0_184:
	s_or_b64 exec, exec, s[4:5]
	s_mov_b64 s[4:5], exec
	v_mbcnt_lo_u32_b32 v0, s4, 0
	v_mbcnt_hi_u32_b32 v0, s5, v0
	v_cmp_eq_u32_e32 vcc, 0, v0
	s_waitcnt vmcnt(0)
	buffer_inv sc1
	s_and_saveexec_b64 s[6:7], vcc
	s_cbranch_execz .LBB0_186
	s_bcnt1_i32_b64 s4, s[4:5]
	v_mov_b32_e32 v0, 0
	v_mov_b32_e32 v1, s4
	s_nop 0

; __device__ __forceinline__ unsigned xb_ld(unsigned* p)              { return __hip_atomic_load(p, __ATOMIC_RELAXED, __HIP_MEMORY_SCOPE_AGENT); }
; __device__ __forceinline__ unsigned xb_add(unsigned* p, unsigned v) { return __hip_atomic_fetch_add(p, v, __ATOMIC_RELAXED, __HIP_MEMORY_SCOPE_AGENT); }
; #define XB_SPIN(cond, bar) do { unsigned _sp = 0; while (cond) { __builtin_amdgcn_s_sleep(1); \
;     if ((++_sp & 255u) == 0u) { if (xb_ld(&(bar)[XB_TMO])) break; if (_sp > XB_SPIN_CAP) { atomicAdd(&(bar)[XB_TMO], 1u); break; } } } } while (0)
; __device__ __forceinline__ void xcd_barrier(const XcdBarrier& b, const bool leader  ) {
;     ...
;         const unsigned old = xb_add(&bar[XB_XSUB(b.x)], 1u);
;         const unsigned gen = old / nloc;
;         if (old + 1u == (gen + 1u) * nloc) {
;             __builtin_amdgcn_fence(__ATOMIC_RELEASE, "agent");
;             asm volatile("s_waitcnt vmcnt(0)" ::: "memory");
;             const unsigned og = xb_add(&bar[XB_TOP], 1u);
;             const unsigned tg = og / nx;
;             if (og + 1u == (tg + 1u) * nx) xb_add(&bar[XB_TOPGEN], 1u);
;             else XB_SPIN(xb_ld(&bar[XB_TOPGEN]) == tg, bar);
;             __builtin_amdgcn_fence(__ATOMIC_ACQUIRE, "agent");
;             xb_add(&bar[XB_XGEN(b.x)], 1u);
;             asm volatile("s_waitcnt vmcnt(0)" ::: "memory");
;         } else {
;             XB_SPIN(xb_ld(&bar[XB_XGEN(b.x)]) == gen, bar);
;             __builtin_amdgcn_fence(__ATOMIC_ACQUIRE, "agent");
;             asm volatile("s_waitcnt vmcnt(0)" ::: "memory");
;         }
.LBB0_378:
	s_or_b64 exec, exec, s[14:15]
	v_cvt_f32_u32_e32 v5, v3
	s_waitcnt vmcnt(0)
	v_readfirstlane_b32 s12, v4
	s_add_u32 s10, s10, 0x2400
	s_addc_u32 s11, s11, 0
	v_rcp_iflag_f32_e32 v5, v5
	v_add_u32_e32 v6, s12, v2
	v_mul_f32_e32 v4, 0x4f7ffffe, v5
	v_cvt_u32_f32_e32 v4, v4
	v_sub_u32_e32 v5, 0, v3
	v_mul_lo_u32 v2, v5, v4
	v_mul_hi_u32 v2, v4, v2
	v_add_u32_e32 v2, v4, v2
	v_mul_hi_u32 v2, v6, v2
	v_mul_lo_u32 v4, v2, v3
	v_sub_u32_e32 v4, v6, v4
	v_add_u32_e32 v5, 1, v2
	v_cmp_ge_u32_e32 vcc, v4, v3
	s_nop 1
	v_cndmask_b32_e32 v2, v2, v5, vcc
	v_sub_u32_e32 v5, v4, v3
	v_cndmask_b32_e32 v4, v4, v5, vcc
	v_add_u32_e32 v5, 1, v2
	v_cmp_ge_u32_e32 vcc, v4, v3
	v_add_u32_e32 v4, 1, v6
	s_nop 0
	v_cndmask_b32_e32 v2, v2, v5, vcc
	v_mul_lo_u32 v5, v3, v2
	v_add_u32_e32 v3, v5, v3
	v_cmp_ne_u32_e32 vcc, v4, v3
	s_and_saveexec_b64 s[12:13], vcc
	s_xor_b64 s[12:13], exec, s[12:13]
	s_cbranch_execz .LBB0_392
	s_waitcnt lgkmcnt(0)
	s_add_u32 s10, s6, 0x7500
	s_addc_u32 s11, s7, 0
	global_load_dword v0, v1, s[10:11] sc1
	s_waitcnt vmcnt(0)
	v_cmp_eq_u32_e32 vcc, v0, v2
	s_and_saveexec_b64 s[14:15], vcc
	s_cbranch_execz .LBB0_391
	s_mov_b32 s20, 1
	s_mov_b64 s[16:17], 0
	s_branch .LBB0_382

; __device__ __forceinline__ unsigned xb_add(unsigned* p, unsigned v) { return __hip_atomic_fetch_add(p, v, __ATOMIC_RELAXED, __HIP_MEMORY_SCOPE_AGENT); }
; __device__ __forceinline__ void xcd_barrier(const XcdBarrier& b, const bool leader  ) {
;     ...
;             __builtin_amdgcn_fence(__ATOMIC_ACQUIRE, "agent");
;             xb_add(&bar[XB_XGEN(b.x)], 1u);
;             asm volatile("s_waitcnt vmcnt(0)" ::: "memory");
.LBB0_409:
	s_or_b64 exec, exec, s[4:5]
	s_mov_b64 s[4:5], exec
	v_mbcnt_lo_u32_b32 v0, s4, 0
	v_mbcnt_hi_u32_b32 v0, s5, v0
	v_cmp_eq_u32_e32 vcc, 0, v0
	s_waitcnt vmcnt(0)
	buffer_inv sc1
	s_and_saveexec_b64 s[6:7], vcc
	s_cbranch_execz .LBB0_411
	s_bcnt1_i32_b64 s4, s[4:5]
	v_mov_b32_e32 v0, s4
	s_nop 0

; __device__ __forceinline__ unsigned xb_ld(unsigned* p)              { return __hip_atomic_load(p, __ATOMIC_RELAXED, __HIP_MEMORY_SCOPE_AGENT); }
; __device__ __forceinline__ unsigned xb_add(unsigned* p, unsigned v) { return __hip_atomic_fetch_add(p, v, __ATOMIC_RELAXED, __HIP_MEMORY_SCOPE_AGENT); }
; #define XB_SPIN(cond, bar) do { unsigned _sp = 0; while (cond) { __builtin_amdgcn_s_sleep(1); \
;     if ((++_sp & 255u) == 0u) { if (xb_ld(&(bar)[XB_TMO])) break; if (_sp > XB_SPIN_CAP) { atomicAdd(&(bar)[XB_TMO], 1u); break; } } } } while (0)
; __device__ __forceinline__ void xcd_barrier(const XcdBarrier& b, const bool leader  ) {
;     ...
;         const unsigned old = xb_add(&bar[XB_XSUB(b.x)], 1u);
;         const unsigned gen = old / nloc;
;         if (old + 1u == (gen + 1u) * nloc) {
;             __builtin_amdgcn_fence(__ATOMIC_RELEASE, "agent");
;             asm volatile("s_waitcnt vmcnt(0)" ::: "memory");
;             const unsigned og = xb_add(&bar[XB_TOP], 1u);
;             const unsigned tg = og / nx;
;             if (og + 1u == (tg + 1u) * nx) xb_add(&bar[XB_TOPGEN], 1u);
;             else XB_SPIN(xb_ld(&bar[XB_TOPGEN]) == tg, bar);
;             __builtin_amdgcn_fence(__ATOMIC_ACQUIRE, "agent");
;             xb_add(&bar[XB_XGEN(b.x)], 1u);
;             asm volatile("s_waitcnt vmcnt(0)" ::: "memory");
;         } else {
;             XB_SPIN(xb_ld(&bar[XB_XGEN(b.x)]) == gen, bar);
;             __builtin_amdgcn_fence(__ATOMIC_ACQUIRE, "agent");
;             asm volatile("s_waitcnt vmcnt(0)" ::: "memory");
;         }
.LBB0_466:
	s_or_b64 exec, exec, s[16:17]
	v_cvt_f32_u32_e32 v5, v3
	s_waitcnt vmcnt(0)
	v_readfirstlane_b32 s14, v4
	s_add_u32 s12, s12, 0x2400
	s_addc_u32 s13, s13, 0
	v_rcp_iflag_f32_e32 v5, v5
	v_add_u32_e32 v6, s14, v2
	v_mul_f32_e32 v4, 0x4f7ffffe, v5
	v_cvt_u32_f32_e32 v4, v4
	v_sub_u32_e32 v5, 0, v3
	v_mul_lo_u32 v2, v5, v4
	v_mul_hi_u32 v2, v4, v2
	v_add_u32_e32 v2, v4, v2
	v_mul_hi_u32 v2, v6, v2
	v_mul_lo_u32 v4, v2, v3
	v_sub_u32_e32 v4, v6, v4
	v_add_u32_e32 v5, 1, v2
	v_cmp_ge_u32_e32 vcc, v4, v3
	s_nop 1
	v_cndmask_b32_e32 v2, v2, v5, vcc
	v_sub_u32_e32 v5, v4, v3
	v_cndmask_b32_e32 v4, v4, v5, vcc
	v_add_u32_e32 v5, 1, v2
	v_cmp_ge_u32_e32 vcc, v4, v3
	v_add_u32_e32 v4, 1, v6
	s_nop 0
	v_cndmask_b32_e32 v2, v2, v5, vcc
	v_mul_lo_u32 v5, v3, v2
	v_add_u32_e32 v3, v5, v3
	v_cmp_ne_u32_e32 vcc, v4, v3
	s_and_saveexec_b64 s[14:15], vcc
	s_xor_b64 s[14:15], exec, s[14:15]
	s_cbranch_execz .LBB0_480
	s_waitcnt lgkmcnt(0)
	s_add_u32 s12, s10, 0x7500
	s_addc_u32 s13, s11, 0
	global_load_dword v0, v1, s[12:13] sc1
	s_waitcnt vmcnt(0)
	v_cmp_eq_u32_e32 vcc, v0, v2
	s_and_saveexec_b64 s[16:17], vcc
	s_cbranch_execz .LBB0_479
	s_mov_b32 s20, 1
	s_mov_b64 s[18:19], 0
	s_branch .LBB0_470

; __device__ __forceinline__ unsigned xb_add(unsigned* p, unsigned v) { return __hip_atomic_fetch_add(p, v, __ATOMIC_RELAXED, __HIP_MEMORY_SCOPE_AGENT); }
; __device__ __forceinline__ void xcd_barrier(const XcdBarrier& b, const bool leader  ) {
;     ...
;             __builtin_amdgcn_fence(__ATOMIC_ACQUIRE, "agent");
;             xb_add(&bar[XB_XGEN(b.x)], 1u);
;             asm volatile("s_waitcnt vmcnt(0)" ::: "memory");
.LBB0_497:
	s_or_b64 exec, exec, s[6:7]
	s_mov_b64 s[6:7], exec
	v_mbcnt_lo_u32_b32 v0, s6, 0
	v_mbcnt_hi_u32_b32 v0, s7, v0
	v_cmp_eq_u32_e32 vcc, 0, v0
	s_waitcnt vmcnt(0)
	buffer_inv sc1
	s_and_saveexec_b64 s[10:11], vcc
	s_cbranch_execz .LBB0_499
	s_bcnt1_i32_b64 s6, s[6:7]
	v_mov_b32_e32 v0, s6
	s_nop 0

; __device__ __forceinline__ unsigned xb_ld(unsigned* p)              { return __hip_atomic_load(p, __ATOMIC_RELAXED, __HIP_MEMORY_SCOPE_AGENT); }
; __device__ __forceinline__ unsigned xb_add(unsigned* p, unsigned v) { return __hip_atomic_fetch_add(p, v, __ATOMIC_RELAXED, __HIP_MEMORY_SCOPE_AGENT); }
; #define XB_SPIN(cond, bar) do { unsigned _sp = 0; while (cond) { __builtin_amdgcn_s_sleep(1); \
;     if ((++_sp & 255u) == 0u) { if (xb_ld(&(bar)[XB_TMO])) break; if (_sp > XB_SPIN_CAP) { atomicAdd(&(bar)[XB_TMO], 1u); break; } } } } while (0)
; __device__ __forceinline__ void xcd_barrier(const XcdBarrier& b, const bool leader  ) {
;     ...
;         const unsigned old = xb_add(&bar[XB_XSUB(b.x)], 1u);
;         const unsigned gen = old / nloc;
;         if (old + 1u == (gen + 1u) * nloc) {
;             __builtin_amdgcn_fence(__ATOMIC_RELEASE, "agent");
;             asm volatile("s_waitcnt vmcnt(0)" ::: "memory");
;             const unsigned og = xb_add(&bar[XB_TOP], 1u);
;             const unsigned tg = og / nx;
;             if (og + 1u == (tg + 1u) * nx) xb_add(&bar[XB_TOPGEN], 1u);
;             else XB_SPIN(xb_ld(&bar[XB_TOPGEN]) == tg, bar);
;             __builtin_amdgcn_fence(__ATOMIC_ACQUIRE, "agent");
;             xb_add(&bar[XB_XGEN(b.x)], 1u);
;             asm volatile("s_waitcnt vmcnt(0)" ::: "memory");
;         } else {
;             XB_SPIN(xb_ld(&bar[XB_XGEN(b.x)]) == gen, bar);
;             __builtin_amdgcn_fence(__ATOMIC_ACQUIRE, "agent");
;             asm volatile("s_waitcnt vmcnt(0)" ::: "memory");
;         }
.LBB0_1232:
	s_or_b64 exec, exec, s[12:13]
	v_cvt_f32_u32_e32 v5, v3
	s_waitcnt vmcnt(0)
	v_readfirstlane_b32 s10, v4
	s_add_u32 s8, s8, 0x2400
	s_addc_u32 s9, s9, 0
	v_rcp_iflag_f32_e32 v5, v5
	v_add_u32_e32 v6, s10, v2
	v_mul_f32_e32 v4, 0x4f7ffffe, v5
	v_cvt_u32_f32_e32 v4, v4
	v_sub_u32_e32 v5, 0, v3
	v_mul_lo_u32 v2, v5, v4
	v_mul_hi_u32 v2, v4, v2
	v_add_u32_e32 v2, v4, v2
	v_mul_hi_u32 v2, v6, v2
	v_mul_lo_u32 v4, v2, v3
	v_sub_u32_e32 v4, v6, v4
	v_add_u32_e32 v5, 1, v2
	v_cmp_ge_u32_e32 vcc, v4, v3
	s_nop 1
	v_cndmask_b32_e32 v2, v2, v5, vcc
	v_sub_u32_e32 v5, v4, v3
	v_cndmask_b32_e32 v4, v4, v5, vcc
	v_add_u32_e32 v5, 1, v2
	v_cmp_ge_u32_e32 vcc, v4, v3
	v_add_u32_e32 v4, 1, v6
	s_nop 0
	v_cndmask_b32_e32 v2, v2, v5, vcc
	v_mul_lo_u32 v5, v3, v2
	v_add_u32_e32 v3, v5, v3
	v_cmp_ne_u32_e32 vcc, v4, v3
	s_and_saveexec_b64 s[10:11], vcc
	s_xor_b64 s[10:11], exec, s[10:11]
	s_cbranch_execz .LBB0_1246
	s_waitcnt lgkmcnt(0)
	s_add_u32 s8, s6, 0x7500
	s_addc_u32 s9, s7, 0
	global_load_dword v0, v1, s[8:9] sc1
	s_waitcnt vmcnt(0)
	v_cmp_eq_u32_e32 vcc, v0, v2
	s_and_saveexec_b64 s[12:13], vcc
	s_cbranch_execz .LBB0_1245
	s_mov_b32 s20, 1
	s_mov_b64 s[14:15], 0
	s_branch .LBB0_1236

; __device__ __forceinline__ unsigned xb_ld(unsigned* p)              { return __hip_atomic_load(p, __ATOMIC_RELAXED, __HIP_MEMORY_SCOPE_AGENT); }
; __device__ __forceinline__ unsigned xb_add(unsigned* p, unsigned v) { return __hip_atomic_fetch_add(p, v, __ATOMIC_RELAXED, __HIP_MEMORY_SCOPE_AGENT); }
; #define XB_SPIN(cond, bar) do { unsigned _sp = 0; while (cond) { __builtin_amdgcn_s_sleep(1); \
;     if ((++_sp & 255u) == 0u) { if (xb_ld(&(bar)[XB_TMO])) break; if (_sp > XB_SPIN_CAP) { atomicAdd(&(bar)[XB_TMO], 1u); break; } } } } while (0)
; __device__ __forceinline__ void xcd_barrier(const XcdBarrier& b, const bool leader  ) {
;     ...
;         const unsigned old = xb_add(&bar[XB_XSUB(b.x)], 1u);
;         const unsigned gen = old / nloc;
;         if (old + 1u == (gen + 1u) * nloc) {
;             __builtin_amdgcn_fence(__ATOMIC_RELEASE, "agent");
;             asm volatile("s_waitcnt vmcnt(0)" ::: "memory");
;             const unsigned og = xb_add(&bar[XB_TOP], 1u);
;             const unsigned tg = og / nx;
;             if (og + 1u == (tg + 1u) * nx) xb_add(&bar[XB_TOPGEN], 1u);
;             else XB_SPIN(xb_ld(&bar[XB_TOPGEN]) == tg, bar);
;             __builtin_amdgcn_fence(__ATOMIC_ACQUIRE, "agent");
;             xb_add(&bar[XB_XGEN(b.x)], 1u);
;             asm volatile("s_waitcnt vmcnt(0)" ::: "memory");
;         } else {
;             XB_SPIN(xb_ld(&bar[XB_XGEN(b.x)]) == gen, bar);
;             __builtin_amdgcn_fence(__ATOMIC_ACQUIRE, "agent");
;             asm volatile("s_waitcnt vmcnt(0)" ::: "memory");
;         }
.LBB0_1704:
	s_or_b64 exec, exec, s[26:27]
	v_cvt_f32_u32_e32 v5, v3
	s_waitcnt vmcnt(0)
	v_readfirstlane_b32 s14, v4
	s_add_u32 s16, s16, 0x2400
	s_addc_u32 s17, s17, 0
	v_rcp_iflag_f32_e32 v5, v5
	v_add_u32_e32 v6, s14, v2
	v_mul_f32_e32 v4, 0x4f7ffffe, v5
	v_cvt_u32_f32_e32 v4, v4
	v_sub_u32_e32 v5, 0, v3
	v_mul_lo_u32 v2, v5, v4
	v_mul_hi_u32 v2, v4, v2
	v_add_u32_e32 v2, v4, v2
	v_mul_hi_u32 v2, v6, v2
	v_mul_lo_u32 v4, v2, v3
	v_sub_u32_e32 v4, v6, v4
	v_add_u32_e32 v5, 1, v2
	v_cmp_ge_u32_e32 vcc, v4, v3
	s_nop 1
	v_cndmask_b32_e32 v2, v2, v5, vcc
	v_sub_u32_e32 v5, v4, v3
	v_cndmask_b32_e32 v4, v4, v5, vcc
	v_add_u32_e32 v5, 1, v2
	v_cmp_ge_u32_e32 vcc, v4, v3
	v_add_u32_e32 v4, 1, v6
	s_nop 0
	v_cndmask_b32_e32 v2, v2, v5, vcc
	v_mul_lo_u32 v5, v3, v2
	v_add_u32_e32 v3, v5, v3
	v_cmp_ne_u32_e32 vcc, v4, v3
	s_and_saveexec_b64 s[14:15], vcc
	s_xor_b64 s[18:19], exec, s[14:15]
	s_cbranch_execz .LBB0_1718
	s_waitcnt lgkmcnt(0)
	s_add_u32 s16, s8, 0x7500
	s_addc_u32 s17, s9, 0
	global_load_dword v0, v1, s[16:17] sc1
	s_waitcnt vmcnt(0)
	v_cmp_eq_u32_e32 vcc, v0, v2
	s_and_saveexec_b64 s[26:27], vcc
	s_cbranch_execz .LBB0_1717
	s_mov_b32 s14, 1
	s_mov_b64 s[30:31], 0
	s_branch .LBB0_1708

; __device__ __forceinline__ unsigned xb_add(unsigned* p, unsigned v) { return __hip_atomic_fetch_add(p, v, __ATOMIC_RELAXED, __HIP_MEMORY_SCOPE_AGENT); }
; __device__ __forceinline__ void xcd_barrier(const XcdBarrier& b, const bool leader  ) {
;     ...
;             __builtin_amdgcn_fence(__ATOMIC_ACQUIRE, "agent");
;             xb_add(&bar[XB_XGEN(b.x)], 1u);
;             asm volatile("s_waitcnt vmcnt(0)" ::: "memory");
.LBB0_1744:
	s_or_b64 exec, exec, s[4:5]
	s_mov_b64 s[4:5], exec
	v_mbcnt_lo_u32_b32 v0, s4, 0
	v_mbcnt_hi_u32_b32 v0, s5, v0
	v_cmp_eq_u32_e32 vcc, 0, v0
	s_waitcnt vmcnt(0)
	buffer_inv sc1
	s_and_saveexec_b64 s[8:9], vcc
	s_cbranch_execz .LBB0_1746
	s_bcnt1_i32_b64 s4, s[4:5]
	v_mov_b32_e32 v0, s4
	s_nop 0

; __device__ __forceinline__ unsigned xb_ld(unsigned* p)              { return __hip_atomic_load(p, __ATOMIC_RELAXED, __HIP_MEMORY_SCOPE_AGENT); }
; __device__ __forceinline__ unsigned xb_add(unsigned* p, unsigned v) { return __hip_atomic_fetch_add(p, v, __ATOMIC_RELAXED, __HIP_MEMORY_SCOPE_AGENT); }
; #define XB_SPIN(cond, bar) do { unsigned _sp = 0; while (cond) { __builtin_amdgcn_s_sleep(1); \
;     if ((++_sp & 255u) == 0u) { if (xb_ld(&(bar)[XB_TMO])) break; if (_sp > XB_SPIN_CAP) { atomicAdd(&(bar)[XB_TMO], 1u); break; } } } } while (0)
; __device__ __forceinline__ void xcd_barrier(const XcdBarrier& b, const bool leader  ) {
;     ...
;         const unsigned old = xb_add(&bar[XB_XSUB(b.x)], 1u);
;         const unsigned gen = old / nloc;
;         if (old + 1u == (gen + 1u) * nloc) {
;             __builtin_amdgcn_fence(__ATOMIC_RELEASE, "agent");
;             asm volatile("s_waitcnt vmcnt(0)" ::: "memory");
;             const unsigned og = xb_add(&bar[XB_TOP], 1u);
;             const unsigned tg = og / nx;
;             if (og + 1u == (tg + 1u) * nx) xb_add(&bar[XB_TOPGEN], 1u);
;             else XB_SPIN(xb_ld(&bar[XB_TOPGEN]) == tg, bar);
;             __builtin_amdgcn_fence(__ATOMIC_ACQUIRE, "agent");
;             xb_add(&bar[XB_XGEN(b.x)], 1u);
;             asm volatile("s_waitcnt vmcnt(0)" ::: "memory");
;         } else {
;             XB_SPIN(xb_ld(&bar[XB_XGEN(b.x)]) == gen, bar);
;             __builtin_amdgcn_fence(__ATOMIC_ACQUIRE, "agent");
;             asm volatile("s_waitcnt vmcnt(0)" ::: "memory");
;         }
.LBB0_1796:
	s_or_b64 exec, exec, s[36:37]
	v_cvt_f32_u32_e32 v5, v3
	s_waitcnt vmcnt(0)
	v_readfirstlane_b32 s14, v4
	s_add_u32 s8, s8, 0x2400
	s_addc_u32 s9, s9, 0
	v_rcp_iflag_f32_e32 v5, v5
	v_add_u32_e32 v6, s14, v2
	v_mul_f32_e32 v4, 0x4f7ffffe, v5
	v_cvt_u32_f32_e32 v4, v4
	v_sub_u32_e32 v5, 0, v3
	v_mul_lo_u32 v2, v5, v4
	v_mul_hi_u32 v2, v4, v2
	v_add_u32_e32 v2, v4, v2
	v_mul_hi_u32 v2, v6, v2
	v_mul_lo_u32 v4, v2, v3
	v_sub_u32_e32 v4, v6, v4
	v_add_u32_e32 v5, 1, v2
	v_cmp_ge_u32_e32 vcc, v4, v3
	s_nop 1
	v_cndmask_b32_e32 v2, v2, v5, vcc
	v_sub_u32_e32 v5, v4, v3
	v_cndmask_b32_e32 v4, v4, v5, vcc
	v_add_u32_e32 v5, 1, v2
	v_cmp_ge_u32_e32 vcc, v4, v3
	v_add_u32_e32 v4, 1, v6
	s_nop 0
	v_cndmask_b32_e32 v2, v2, v5, vcc
	v_mul_lo_u32 v5, v3, v2
	v_add_u32_e32 v3, v5, v3
	v_cmp_ne_u32_e32 vcc, v4, v3
	s_and_saveexec_b64 s[22:23], vcc
	s_xor_b64 s[30:31], exec, s[22:23]
	s_cbranch_execz .LBB0_1810
	s_waitcnt lgkmcnt(0)
	s_add_u32 s8, s6, 0x7500
	s_addc_u32 s9, s7, 0
	global_load_dword v0, v1, s[8:9] sc1
	s_waitcnt vmcnt(0)
	v_cmp_eq_u32_e32 vcc, v0, v2
	s_and_saveexec_b64 s[36:37], vcc
	s_cbranch_execz .LBB0_1809
	s_mov_b32 s14, 1
	s_mov_b64 s[38:39], 0
	s_branch .LBB0_1800

; __device__ __forceinline__ unsigned xb_ld(unsigned* p)              { return __hip_atomic_load(p, __ATOMIC_RELAXED, __HIP_MEMORY_SCOPE_AGENT); }
; __device__ __forceinline__ unsigned xb_add(unsigned* p, unsigned v) { return __hip_atomic_fetch_add(p, v, __ATOMIC_RELAXED, __HIP_MEMORY_SCOPE_AGENT); }
; #define XB_SPIN(cond, bar) do { unsigned _sp = 0; while (cond) { __builtin_amdgcn_s_sleep(1); \
;     if ((++_sp & 255u) == 0u) { if (xb_ld(&(bar)[XB_TMO])) break; if (_sp > XB_SPIN_CAP) { atomicAdd(&(bar)[XB_TMO], 1u); break; } } } } while (0)
; __device__ __forceinline__ void xcd_barrier(const XcdBarrier& b, const bool leader  ) {
;     ...
;         const unsigned old = xb_add(&bar[XB_XSUB(b.x)], 1u);
;         const unsigned gen = old / nloc;
;         if (old + 1u == (gen + 1u) * nloc) {
;             __builtin_amdgcn_fence(__ATOMIC_RELEASE, "agent");
;             asm volatile("s_waitcnt vmcnt(0)" ::: "memory");
;             const unsigned og = xb_add(&bar[XB_TOP], 1u);
;             const unsigned tg = og / nx;
;             if (og + 1u == (tg + 1u) * nx) xb_add(&bar[XB_TOPGEN], 1u);
;             else XB_SPIN(xb_ld(&bar[XB_TOPGEN]) == tg, bar);
;             __builtin_amdgcn_fence(__ATOMIC_ACQUIRE, "agent");
;             xb_add(&bar[XB_XGEN(b.x)], 1u);
;             asm volatile("s_waitcnt vmcnt(0)" ::: "memory");
;         } else {
;             XB_SPIN(xb_ld(&bar[XB_XGEN(b.x)]) == gen, bar);
;             __builtin_amdgcn_fence(__ATOMIC_ACQUIRE, "agent");
;             asm volatile("s_waitcnt vmcnt(0)" ::: "memory");
;         }
.LBB0_1988:
	s_or_b64 exec, exec, s[36:37]
	v_cvt_f32_u32_e32 v5, v3
	s_waitcnt vmcnt(0)
	v_readfirstlane_b32 s14, v4
	s_add_u32 s8, s8, 0x2400
	s_addc_u32 s9, s9, 0
	v_rcp_iflag_f32_e32 v5, v5
	v_add_u32_e32 v6, s14, v2
	v_mul_f32_e32 v4, 0x4f7ffffe, v5
	v_cvt_u32_f32_e32 v4, v4
	v_sub_u32_e32 v5, 0, v3
	v_mul_lo_u32 v2, v5, v4
	v_mul_hi_u32 v2, v4, v2
	v_add_u32_e32 v2, v4, v2
	v_mul_hi_u32 v2, v6, v2
	v_mul_lo_u32 v4, v2, v3
	v_sub_u32_e32 v4, v6, v4
	v_add_u32_e32 v5, 1, v2
	v_cmp_ge_u32_e32 vcc, v4, v3
	s_nop 1
	v_cndmask_b32_e32 v2, v2, v5, vcc
	v_sub_u32_e32 v5, v4, v3
	v_cndmask_b32_e32 v4, v4, v5, vcc
	v_add_u32_e32 v5, 1, v2
	v_cmp_ge_u32_e32 vcc, v4, v3
	v_add_u32_e32 v4, 1, v6
	s_nop 0
	v_cndmask_b32_e32 v2, v2, v5, vcc
	v_mul_lo_u32 v5, v3, v2
	v_add_u32_e32 v3, v5, v3
	v_cmp_ne_u32_e32 vcc, v4, v3
	s_and_saveexec_b64 s[16:17], vcc
	s_xor_b64 s[30:31], exec, s[16:17]
	s_cbranch_execz .LBB0_2002
	s_waitcnt lgkmcnt(0)
	s_add_u32 s8, s6, 0x7500
	s_addc_u32 s9, s7, 0
	global_load_dword v0, v1, s[8:9] sc1
	s_waitcnt vmcnt(0)
	v_cmp_eq_u32_e32 vcc, v0, v2
	s_and_saveexec_b64 s[36:37], vcc
	s_cbranch_execz .LBB0_2001
	s_mov_b32 s14, 1
	s_mov_b64 s[38:39], 0
	s_branch .LBB0_1992

; __device__ __forceinline__ unsigned xb_add(unsigned* p, unsigned v) { return __hip_atomic_fetch_add(p, v, __ATOMIC_RELAXED, __HIP_MEMORY_SCOPE_AGENT); }
; __device__ __forceinline__ void xcd_barrier(const XcdBarrier& b, const bool leader  ) {
;     ...
;             __builtin_amdgcn_fence(__ATOMIC_ACQUIRE, "agent");
;             xb_add(&bar[XB_XGEN(b.x)], 1u);
;             asm volatile("s_waitcnt vmcnt(0)" ::: "memory");
.LBB0_2081:
	s_or_b64 exec, exec, s[4:5]
	s_mov_b64 s[4:5], exec
	v_mbcnt_lo_u32_b32 v0, s4, 0
	v_mbcnt_hi_u32_b32 v0, s5, v0
	v_cmp_eq_u32_e32 vcc, 0, v0
	s_waitcnt vmcnt(0)
	buffer_inv sc1
	s_and_saveexec_b64 s[6:7], vcc
	s_cbranch_execz .LBB0_1749
	s_bcnt1_i32_b64 s4, s[4:5]
	v_mov_b32_e32 v0, s4
	s_nop 0
	s_branch .LBB0_1749
